# attention half-step 1: QK region rescheduled; mask load and K/V prefetch (tile t+1) issued at the top of the region
# speedup vs baseline: 1.0111x; 1.0041x over previous
; __device__ __forceinline__ int v_st(int k, int c) { const int kk = (k & ~0xC) | ((k & 4) << 1) | ((k & 8) >> 1); return ((kk >> 3) * 4 + (c >> 5)) * 512 + ((kk & 7) * 32 + (c & 31)) * 2; }
; __device__ __forceinline__ int v_rd_base(int lane) { return ((lane & 3) << 3) | (((lane >> 2) & 3) << 6) | (((lane >> 4) & 1) << 5) | (((lane >> 5) & 1) << 8); }
; #define VMW() asm volatile("s_waitcnt vmcnt(0)" ::: "memory")
; #define SWRITE_HK(bf) do { *(bf16x8*)(K_lds + (bf) * SHM_K + kws) = S.st_k0; *(bf16x8*)(K_lds + (bf) * SHM_K + kws + 32 * 256) = S.st_k1; } while (0)
; __device__ __forceinline__ void attn_prime(const BlockRef& cur, char* lds, Seam& S) {
;     const int tid = threadIdx.x, wid = __builtin_amdgcn_readfirstlane(tid >> 6), lane = tid & 63, r32 = lane & 31, hi = lane >> 5;
;     const int sr = tid >> 4, sc = (tid & 15) * 8, kws = KSWZ(sr, sc * 2); char* K_lds = lds + 2 * SHM_V;
; #pragma unroll
;     for (int d0 = 0; d0 < 8; ++d0) S.qr[d0] = load8(cur.Q + (size_t)(wid * QBLK + r32) * LD + d0 * 16 + hi * 8);
;     SLOAD_H(cur.K, cur.V, 0); VMW(); SWRITE_HK(0);
;     __syncthreads();
; }
; __device__ __forceinline__ void attn_block(const BlockRef& cur, const BlockRef& nxt, char* lds, Seam& S) {
;     const int tid = threadIdx.x, wid = __builtin_amdgcn_readfirstlane(tid >> 6), lane = tid & 63, r32 = lane & 31, hi = lane >> 5;
;     const int NT = (cur.P0 + QB - 1) / KVBLK + 1;
;     char* V_lds = lds; char* K_lds = lds + 2 * SHM_V;
;     float* ws = (float*)(lds + 2 * SHM_V + 2 * SHM_K) + wid * 64; float* li_l = ws, * al_l = ws + 32;
;     float m_reg = -1e30f, l_reg = 0; f32x16 o[4] = {};
;     const int sr = tid >> 4, sc = (tid & 15) * 8, vst0 = v_st(sr, sc), vst1 = v_st(32 + sr, sc), kws = KSWZ(sr, sc * 2);
;     const int vb0 = (int)(uintptr_t)V_lds + v_rd_base(lane);
;     const bf16* Kh = cur.K; const bf16* Vh = cur.V;
;     const unsigned mrow_off = (unsigned)(wid * QBLK + r32) * 512u;
; __device__ __forceinline__ void attn_phase(char* lds, const bf16* Q, const bf16* K, const bf16* V, bf16* O, const unsigned long long* MW, int first, int stride) {
;     constexpr int total = (DUP_PHASE == 5) ? 1024 : 512;
;     int L = first; if (L >= total) return;
;     Item it = decode(L); int pass = 0;
;     BlockRef cur = mkref(it, 0, Q, K, V, O, MW);
;     Seam S;
;     attn_prime(cur, lds, S);
.LBB0_1289:
	s_cmp_lt_i32 s54, 6
	s_cselect_b64 s[8:9], -1, 0
	s_and_b64 s[0:1], s[8:9], s[0:1]
	s_andn2_b64 vcc, exec, s[0:1]
	s_cbranch_vccnz .LBB0_1447
	s_cmpk_gt_i32 s2, 0x1ff
	s_cbranch_scc1 .LBB0_1447
	s_add_u32 s3, s52, 0xc000000
	s_addc_u32 s15, s53, 0
	s_add_u32 s33, s52, 0x10000000
	s_addc_u32 s35, s53, 0
	s_add_u32 s56, s52, 0x14000000
	s_addc_u32 s57, s53, 0
	s_add_u32 s58, s52, 0x2e00000
	s_addc_u32 s59, s53, 0
	s_lshl_b32 s4, s2, 3
	s_bfe_u32 s1, s2, 0x30003
	s_and_b32 s4, s4, 56
	s_lshl_b32 s5, s4, 9
	s_lshl_b32 s38, s1, 8
	s_bfe_u32 s0, s2, 0x30006
	s_xor_b32 s73, s1, 15
	s_or_b32 s1, s5, s38
	s_or_b32 s72, s4, s0
	s_lshl_b32 s5, s1, 11
	s_add_u32 s6, s3, s5
	s_addc_u32 s7, s15, 0
	s_lshl_b32 s0, s0, 8
	s_add_u32 s10, s6, s0
	s_addc_u32 s11, s7, 0
	s_add_u32 s5, s30, s5
	s_addc_u32 s6, s31, 0
	s_add_u32 s66, s5, s0
	s_addc_u32 s67, s6, 0
	s_lshl_b32 s4, s4, 20
	s_add_u32 s5, s33, s4
	s_addc_u32 s7, s35, 0
	s_add_u32 s6, s5, s0
	s_addc_u32 s7, s7, 0
	s_add_u32 s4, s56, s4
	s_addc_u32 s5, s57, 0
	s_add_u32 s70, s4, s0
	s_addc_u32 s71, s5, 0
	s_lshl_b32 s0, s1, 9
	s_add_u32 s68, s58, s0
	v_readfirstlane_b32 s0, v0
	s_addc_u32 s69, s59, 0
	s_lshr_b32 s0, s0, 1
	s_waitcnt vmcnt(0)
	v_and_b32_e32 v30, 31, v0
	s_and_b32 s0, s0, 0x7fffffe0
	v_or_b32_e32 v166, s0, v30
	v_mov_b32_e32 v167, 0
	v_lshlrev_b64 v[2:3], 11, v[166:167]
	v_lshrrev_b32_e32 v1, 1, v0
	v_lshl_add_u64 v[2:3], s[10:11], 0, v[2:3]
	v_and_b32_e32 v166, 16, v1
	v_lshrrev_b32_e32 v1, 4, v0
	v_lshlrev_b32_e32 v13, 3, v0
	v_lshl_add_u64 v[10:11], v[2:3], 0, v[166:167]
	v_and_b32_e32 v12, 0x78, v13
	v_lshlrev_b32_e32 v166, 11, v1
	v_lshlrev_b32_e32 v14, 1, v12
	v_mov_b32_e32 v15, v167
	v_lshl_add_u64 v[2:3], s[6:7], 0, v[166:167]
	s_mov_b32 s0, 0x10000
	v_lshl_add_u64 v[16:17], v[2:3], 0, v[14:15]
	v_add_co_u32_e32 v18, vcc, s0, v16
	v_bfe_u32 v21, v0, 4, 2
	s_nop 0
	v_addc_co_u32_e32 v19, vcc, 0, v17, vcc
	global_load_dwordx4 v[2:5], v[16:17], off
	global_load_dwordx4 v[6:9], v[18:19], off
	global_load_dwordx4 v[126:129], v[10:11], off
	global_load_dwordx4 v[122:125], v[10:11], off offset:32
	global_load_dwordx4 v[118:121], v[10:11], off offset:64
	global_load_dwordx4 v[114:117], v[10:11], off offset:96
	global_load_dwordx4 v[110:113], v[10:11], off offset:128
	global_load_dwordx4 v[106:109], v[10:11], off offset:160
	global_load_dwordx4 v[102:105], v[10:11], off offset:192
	global_load_dwordx4 v[98:101], v[10:11], off offset:224
	v_lshl_add_u64 v[10:11], s[70:71], 0, v[166:167]
	v_lshrrev_b32_e32 v18, 3, v0
	v_lshl_add_u64 v[10:11], v[10:11], 0, v[14:15]
	v_lshrrev_b32_e32 v19, 5, v0
	v_and_b32_e32 v25, 8, v18
	v_add_co_u32_e32 v18, vcc, s0, v10
	v_and_or_b32 v21, v19, 4, v21
	s_nop 0
	v_addc_co_u32_e32 v19, vcc, 0, v11, vcc
	global_load_dwordx4 v[130:133], v[10:11], off
	global_load_dwordx4 v[134:137], v[18:19], off
	s_movk_i32 s1, 0x70
	v_lshlrev_b32_e32 v24, 8, v1
	v_lshlrev_b32_e32 v16, 10, v1
	v_or_b32_e32 v27, 32, v1
	v_and_or_b32 v1, v1, 16, v25
	v_bitop3_b32 v15, v14, v0, s1 bitop3:0x78
	v_lshrrev_b32_e32 v20, 5, v162
	v_bfe_u32 v26, v13, 5, 2
	v_lshrrev_b32_e32 v1, 1, v1
	v_add3_u32 v15, 0, v24, v15
	v_lshlrev_b32_e32 v22, 4, v0
	v_and_or_b32 v11, v27, 48, v25
	v_or_b32_e32 v1, v1, v26
	s_waitcnt vmcnt(0)
	v_and_b32_e32 v17, 0x70, v0
	v_lshlrev_b32_e32 v10, 6, v21
	v_and_b32_e32 v18, 48, v14
	v_lshrrev_b32_e32 v11, 1, v11
	v_lshlrev_b32_e32 v1, 9, v1
	v_lshlrev_b32_e32 v23, 1, v0
	v_bitop3_b32 v14, v14, v24, v17 bitop3:0xde
	v_or_b32_e32 v11, v11, v26
	v_or3_b32 v17, v1, v10, v18
	v_and_b32_e32 v1, 0x118, v13
	v_and_b32_e32 v13, 1, v0
	v_and_b32_e32 v28, 0xc0, v22
	v_and_b32_e32 v23, 32, v23
	v_lshlrev_b32_e32 v11, 9, v11
	s_cmp_lg_u32 0, -1
	v_cmp_eq_u32_e64 s[4:5], 0, v13
	v_and_b32_e32 v13, 15, v0
	v_or3_b32 v10, v11, v10, v18
	v_or3_b32 v1, v23, v28, v1
	s_cselect_b32 s0, 0, 0
	v_lshlrev_b32_e32 v170, 4, v13
	v_lshlrev_b32_e32 v13, 7, v0
	s_mov_b32 s13, 0
	v_add_u32_e32 v1, s0, v1
	v_lshlrev_b32_e32 v163, 2, v20
	v_cmp_gt_u32_e64 s[0:1], 32, v162
	v_lshlrev_b32_e32 v168, 13, v20
	s_waitcnt vmcnt(11)
	ds_write_b128 v15, v[2:5] offset:32768
	s_waitcnt vmcnt(10)
	ds_write_b128 v15, v[6:9] offset:40960
	v_lshlrev_b32_e32 v2, 4, v20
	v_and_b32_e32 v4, 0x70, v22
	v_or_b32_e32 v6, 32, v2
	v_xad_u32 v7, v6, v4, 0
	v_or_b32_e32 v6, 64, v2
	v_xad_u32 v5, v2, v4, 0
	v_xad_u32 v9, v6, v4, 0
	v_or_b32_e32 v2, 0x60, v2
	v_lshlrev_b32_e32 v6, 10, v27
	v_lshlrev_b32_e32 v3, 8, v30
	v_xad_u32 v11, v2, v4, 0
	v_or_b32_e32 v2, 0x10000, v16
	v_or_b32_e32 v4, 0x18000, v16
	v_lshlrev_b32_e32 v8, 3, v20
	v_lshlrev_b32_e32 v178, 1, v6
	v_mbcnt_lo_u32_b32 v6, -1, 0
	v_mov_b32_e32 v169, v167
	v_lshl_or_b32 v254, v30, 9, 16
	v_mov_b32_e32 v171, v167
	v_and_b32_e32 v252, 0xf800, v13
	v_mov_b32_e32 v253, v167
	s_mov_b32 s74, 0xff800000
	s_mov_b32 s75, 0x41000000
	s_mov_b32 s14, 0x3e0293ee
	s_mov_b32 s76, 0x40000
	s_mov_b32 s77, 0x50000
	s_mov_b64 s[16:17], 0x40000
	s_mov_b64 s[100:101], 0x50000
	v_lshlrev_b32_e32 v164, 1, v16
	v_lshlrev_b32_e32 v176, 1, v12
	v_lshlrev_b32_e32 v180, 1, v8
	v_mbcnt_hi_u32_b32 v196, -1, v6
	v_lshlrev_b32_e32 v166, 1, v30
	v_add_u32_e32 v197, 0, v17
	v_add_u32_e32 v198, 0, v10
	v_lshlrev_b32_e32 v182, 1, v2
	v_lshlrev_b32_e32 v184, 1, v4
	v_add_u32_e32 v199, v5, v3
	v_add_u32_e32 v200, v7, v3
	v_add_u32_e32 v201, v9, v3
	v_add_u32_e32 v202, v11, v3
	v_mov_b32_e32 v203, 0xf149f2ca
	v_add_u32_e32 v204, 0, v14
	s_mov_b32 s79, 0
	s_mov_b32 s78, s2
	s_waitcnt lgkmcnt(0)
	s_barrier
	s_branch .LBB0_1293

; __device__ __forceinline__ void finishSM(f32x16& p0, f32x16& p1, float alpha, float& l_reg, bf16x8& pa0, bf16x8& pa1, bf16x8& pa2, bf16x8& pa3) {
; #pragma unroll
;     for (int r = 0; r < 16; ++r) p1[r] = __builtin_amdgcn_exp2f(p1[r]);
;     float ps = 0;
; #pragma unroll
;     for (int r = 0; r < 16; ++r) ps += p0[r];
; #pragma unroll
;     for (int r = 0; r < 16; ++r) ps += p1[r];
;     { auto rr = __builtin_amdgcn_permlane32_swap(__float_as_uint(ps), __float_as_uint(ps), false, false);
;       ps = __uint_as_float(rr[0]) + __uint_as_float(rr[1]); }
;     l_reg = l_reg * alpha + ps;
;     ...
;     PK4(p0, 0, pa0); PK4(p0, 8, pa1); PK4(p1, 0, pa2); PK4(p1, 8, pa3);
;     ...
; }
; template <int KB>
; __device__ __forceinline__ void qkt(f32x16& p0, f32x16& p1, const char* K_lds, int r32, int hi, const bf16x8* qr) {
;     p0 = f32x16{}; p1 = f32x16{};
;     const char* kb[4];
; #pragma unroll
;     for (int dd = 0; dd < 4; ++dd) kb[dd] = K_lds + KB * SHM_K + KSWZ(r32, (dd * 16 + hi * 8) * 2);
; #pragma unroll
;     for (int d0 = 0; d0 < 8; ++d0) { const char* a = kb[d0 & 3] + (d0 >> 2) * 128;
;         bf16x8 b0 = *reinterpret_cast<const bf16x8*>(a);
;         bf16x8 b1 = *reinterpret_cast<const bf16x8*>(a + 32 * 256);
;         p0 = __builtin_amdgcn_mfma_f32_32x32x16_bf16(b0, qr[d0], p0, 0, 0, 0);
;         p1 = __builtin_amdgcn_mfma_f32_32x32x16_bf16(b1, qr[d0], p1, 0, 0, 0); }
; }
.LBB0_1299:
	v_add_u32_e32 v146, -8, v179
	global_load_dwordx2 v[146:147], v146, s[68:69]
	v_lshl_add_u64 v[130:131], v[188:189], 0, v[170:171]
	v_lshl_add_u64 v[138:139], v[190:191], 0, v[170:171]
	v_lshl_add_u64 v[134:135], v[130:131], 0, s[100:101]
	v_lshl_add_u64 v[130:131], v[130:131], 0, s[16:17]
	v_lshl_add_u64 v[142:143], v[138:139], 0, s[100:101]
	v_lshl_add_u64 v[138:139], v[138:139], 0, s[16:17]
	global_load_dwordx4 v[130:133], v[130:131], off
	global_load_dwordx4 v[134:137], v[134:135], off
	global_load_dwordx4 v[138:141], v[138:139], off
	global_load_dwordx4 v[142:145], v[142:143], off
	ds_read_b128 v[66:69], v199 offset:49152
	ds_read_b128 v[82:85], v199 offset:57344
	ds_read_b128 v[172:175], v200 offset:49152
	ds_read_b128 v[232:235], v200 offset:57344
	ds_read_b128 v[236:239], v201 offset:49152
	ds_read_b128 v[240:243], v201 offset:57344
	ds_read_b128 v[244:247], v202 offset:49152
	v_exp_f32_e32 v209, v150
	v_add_f32_e32 v150, 0, v219
	v_add_f32_e32 v150, v220, v150
	v_add_f32_e32 v150, v221, v150
	s_waitcnt lgkmcnt(6)
	v_mfma_f32_32x32x16_bf16 v[66:81], v[66:69], v[126:129], 0
	v_add_f32_e32 v150, v222, v150
	v_add_f32_e32 v150, v223, v150
	v_add_f32_e32 v150, v225, v150
	v_add_f32_e32 v150, v224, v150
	v_add_f32_e32 v150, v226, v150
	s_waitcnt lgkmcnt(5)
	v_mfma_f32_32x32x16_bf16 v[82:97], v[82:85], v[126:129], 0
	v_add_f32_e32 v150, v211, v150
	v_add_f32_e32 v150, v212, v150
	v_exp_f32_e32 v194, v194
	s_waitcnt lgkmcnt(4)
	v_mfma_f32_32x32x16_bf16 v[66:81], v[172:175], v[122:125], v[66:81]
	ds_read_b128 v[172:175], v202 offset:57344
	v_exp_f32_e32 v195, v195
	v_exp_f32_e32 v192, v192
	v_exp_f32_e32 v193, v193
	s_waitcnt lgkmcnt(4)
	v_mfma_f32_32x32x16_bf16 v[82:97], v[232:235], v[122:125], v[82:97]
	ds_read_b128 v[232:235], v199 offset:49280
	v_exp_f32_e32 v158, v158
	v_exp_f32_e32 v159, v159
	s_waitcnt lgkmcnt(4)
	v_mfma_f32_32x32x16_bf16 v[66:81], v[236:239], v[118:121], v[66:81]
	ds_read_b128 v[236:239], v199 offset:57472
	v_exp_f32_e32 v207, v154
	v_exp_f32_e32 v208, v155
	v_exp_f32_e32 v210, v151
	s_waitcnt lgkmcnt(4)
	v_mfma_f32_32x32x16_bf16 v[82:97], v[240:243], v[118:121], v[82:97]
	ds_read_b128 v[240:243], v200 offset:49280
	v_exp_f32_e32 v160, v160
	v_exp_f32_e32 v161, v161
	s_waitcnt lgkmcnt(4)
	v_mfma_f32_32x32x16_bf16 v[66:81], v[244:247], v[114:117], v[66:81]
	ds_read_b128 v[244:247], v200 offset:57472
	v_exp_f32_e32 v227, v156
	v_cvt_pk_bf16_f32 v151, v224, v226
	v_cvt_pk_bf16_f32 v154, v214, v216
	v_cvt_pk_bf16_f32 v155, v217, v218
	v_cvt_pk_bf16_f32 v156, v194, v195
	s_waitcnt lgkmcnt(4)
	v_mfma_f32_32x32x16_bf16 v[82:97], v[172:175], v[114:117], v[82:97]
	ds_read_b128 v[172:175], v201 offset:49280
	v_exp_f32_e32 v228, v157
	v_exp_f32_e32 v229, v152
	s_waitcnt lgkmcnt(4)
	v_mfma_f32_32x32x16_bf16 v[66:81], v[232:235], v[110:113], v[66:81]
	ds_read_b128 v[232:235], v201 offset:57472
	v_exp_f32_e32 v230, v153
	v_cvt_pk_bf16_f32 v152, v211, v212
	v_cvt_pk_bf16_f32 v153, v213, v215
	v_cvt_pk_bf16_f32 v157, v192, v193
	v_cvt_pk_bf16_f32 v211, v229, v230
	s_waitcnt lgkmcnt(4)
	v_mfma_f32_32x32x16_bf16 v[82:97], v[236:239], v[110:113], v[82:97]
	ds_read_b128 v[236:239], v202 offset:49280
	v_permlane32_swap_b32_e32 v152, v154
	v_permlane32_swap_b32_e32 v153, v155
	v_add_f32_e32 v249, v213, v150
	v_add_f32_e32 v249, v215, v249
	v_add_f32_e32 v249, v214, v249
	s_waitcnt lgkmcnt(4)
	v_mfma_f32_32x32x16_bf16 v[66:81], v[240:243], v[106:109], v[66:81]
	ds_read_b128 v[240:243], v202 offset:57472
	v_add_f32_e32 v249, v216, v249
	v_add_f32_e32 v249, v217, v249
	v_add_f32_e32 v249, v218, v249
	v_add_f32_e32 v249, v194, v249
	v_add_f32_e32 v248, v195, v249
	s_waitcnt lgkmcnt(4)
	v_mfma_f32_32x32x16_bf16 v[82:97], v[244:247], v[106:109], v[82:97]
	v_add_f32_e32 v248, v192, v248
	v_add_f32_e32 v248, v193, v248
	v_add_f32_e32 v248, v158, v248
	v_add_f32_e32 v248, v159, v248
	v_add_f32_e32 v248, v207, v248
	s_waitcnt lgkmcnt(3)
	v_mfma_f32_32x32x16_bf16 v[66:81], v[172:175], v[102:105], v[66:81]
	v_add_f32_e32 v248, v208, v248
	v_add_f32_e32 v248, v209, v248
	v_add_f32_e32 v248, v210, v248
	v_add_f32_e32 v248, v160, v248
	v_add_f32_e32 v248, v161, v248
	s_waitcnt lgkmcnt(2)
	v_mfma_f32_32x32x16_bf16 v[82:97], v[232:235], v[102:105], v[82:97]
	v_add_f32_e32 v248, v227, v248
	v_add_f32_e32 v248, v228, v248
	v_add_f32_e32 v248, v229, v248
	v_add_f32_e32 v181, v230, v248
	v_mov_b32_e32 v187, v181
	s_waitcnt lgkmcnt(1)
	v_mfma_f32_32x32x16_bf16 v[66:81], v[236:239], v[98:101], v[66:81]
	v_cvt_pk_bf16_f32 v148, v219, v220
	v_cvt_pk_bf16_f32 v149, v221, v222
	v_cvt_pk_bf16_f32 v150, v223, v225
	v_cvt_pk_bf16_f32 v158, v158, v159
	v_cvt_pk_bf16_f32 v159, v207, v208
	s_waitcnt lgkmcnt(0)
	v_mfma_f32_32x32x16_bf16 v[82:97], v[240:243], v[98:101], v[82:97]
	v_cvt_pk_bf16_f32 v208, v209, v210
	v_cvt_pk_bf16_f32 v210, v227, v228
	v_permlane32_swap_b32_e32 v181, v187
	v_permlane32_swap_b32_e32 v148, v150
	v_permlane32_swap_b32_e32 v149, v151
	v_cvt_pk_bf16_f32 v209, v160, v161
	v_permlane32_swap_b32_e32 v208, v210
	v_permlane32_swap_b32_e32 v156, v158
	v_permlane32_swap_b32_e32 v157, v159
	v_permlane32_swap_b32_e32 v209, v211
	v_lshl_add_u64 v[194:195], v[188:189], 0, v[170:171]
	v_lshl_add_u64 v[192:193], v[190:191], 0, v[170:171]
	ds_read_b64_tr_b16 v[172:173], v1 offset:0
	ds_read_b64_tr_b16 v[174:175], v1 offset:0x800
	ds_read_b64_tr_b16 v[212:213], v1 offset:0x1000
	ds_read_b64_tr_b16 v[214:215], v1 offset:0x1800
	ds_read_b64_tr_b16 v[216:217], v1 offset:0x2000
	ds_read_b64_tr_b16 v[218:219], v1 offset:0x2800
	ds_read_b64_tr_b16 v[220:221], v1 offset:0x3000
	ds_read_b64_tr_b16 v[222:223], v1 offset:0x3800
	s_waitcnt lgkmcnt(0)
; __device__ __forceinline__ void sel_mask_tile(f32x16& p0, f32x16& p1, unsigned wlo, unsigned whi, int hi) {
;     const unsigned NEGB = 0xff800000u;
;     const unsigned lo = wlo >> (4 * hi), h2 = whi >> (4 * hi);
; #pragma unroll
;     for (int r = 0; r < 16; ++r) {
;         const int c = (r & 3) + 8 * (r >> 2);
;         const unsigned m0 = (unsigned)__builtin_amdgcn_sbfe((int)lo, c, 1), m1 = (unsigned)__builtin_amdgcn_sbfe((int)h2, c, 1);
;         p0[r] = __uint_as_float((__float_as_uint(p0[r]) & m0) | (NEGB & ~m0));
;         p1[r] = __uint_as_float((__float_as_uint(p1[r]) & m1) | (NEGB & ~m1));
;     }
; }
; __device__ __forceinline__ void partialSM(f32x16& p0, f32x16& p1, float& m_reg, float& mn, float& alpha) {
;     float pmax = p0[0];
; #pragma unroll
;     for (int r = 1; r < 16; ++r) pmax = fmaxf(pmax, p0[r]);
; #pragma unroll
;     for (int r = 0; r < 16; ++r) pmax = fmaxf(pmax, p1[r]);
;     { auto rr = __builtin_amdgcn_permlane32_swap(__float_as_uint(pmax), __float_as_uint(pmax), false, false);
;       pmax = fmaxf(__uint_as_float(rr[0]), __uint_as_float(rr[1])); }
;     constexpr float C2 = 1.4426950408889634f * SCALE;
;     if (__builtin_expect(__all((pmax - m_reg) * SCALE <= THR), 1)) { mn = m_reg; alpha = 1.f; }
;     else { mn = fmaxf(m_reg, pmax); alpha = __builtin_amdgcn_exp2f((m_reg - mn) * C2); m_reg = mn; }
; template <int VB>
; __device__ __forceinline__ void pv_tile(f32x16* o, int vb0, bf16x8 pa0, bf16x8 pa1, bf16x8 pa2, bf16x8 pa3) {
;     ...
;     PV_D0(0); PV_D0(1); PV_D0(2); PV_D0(3);
	s_nop 0
	v_mfma_f32_32x32x16_bf16 v[2:17], v[148:151], v[172:175], v[2:17]
	ds_read_b64_tr_b16 v[172:173], v1 offset:0x200
	ds_read_b64_tr_b16 v[174:175], v1 offset:0xa00
	v_mfma_f32_32x32x16_bf16 v[2:17], v[152:155], v[212:215], v[2:17]
	ds_read_b64_tr_b16 v[212:213], v1 offset:0x1200
	ds_read_b64_tr_b16 v[214:215], v1 offset:0x1a00
	v_mfma_f32_32x32x16_bf16 v[2:17], v[156:159], v[216:219], v[2:17]
	ds_read_b64_tr_b16 v[216:217], v1 offset:0x2200
	ds_read_b64_tr_b16 v[218:219], v1 offset:0x2a00
	ds_read_b64_tr_b16 v[224:225], v1 offset:0x3200
	ds_read_b64_tr_b16 v[226:227], v1 offset:0x3a00
	s_waitcnt lgkmcnt(0)
	v_mfma_f32_32x32x16_bf16 v[2:17], v[208:211], v[220:223], v[2:17]
	v_mfma_f32_32x32x16_bf16 v[50:65], v[148:151], v[172:175], v[50:65]
	ds_read_b64_tr_b16 v[172:173], v1 offset:0x400
	ds_read_b64_tr_b16 v[174:175], v1 offset:0xc00
	v_mfma_f32_32x32x16_bf16 v[50:65], v[152:155], v[212:215], v[50:65]
	ds_read_b64_tr_b16 v[212:213], v1 offset:0x1400
	ds_read_b64_tr_b16 v[214:215], v1 offset:0x1c00
	v_mfma_f32_32x32x16_bf16 v[50:65], v[156:159], v[216:219], v[50:65]
	ds_read_b64_tr_b16 v[216:217], v1 offset:0x2400
	ds_read_b64_tr_b16 v[218:219], v1 offset:0x2c00
	ds_read_b64_tr_b16 v[220:221], v1 offset:0x3400
	ds_read_b64_tr_b16 v[222:223], v1 offset:0x3c00
	s_waitcnt lgkmcnt(0)
	v_mfma_f32_32x32x16_bf16 v[50:65], v[208:211], v[224:227], v[50:65]
	v_mfma_f32_32x32x16_bf16 v[34:49], v[148:151], v[172:175], v[34:49]
	ds_read_b64_tr_b16 v[172:173], v1 offset:0x600
	ds_read_b64_tr_b16 v[174:175], v1 offset:0xe00
	v_mfma_f32_32x32x16_bf16 v[34:49], v[152:155], v[212:215], v[34:49]
	ds_read_b64_tr_b16 v[212:213], v1 offset:0x1600
	ds_read_b64_tr_b16 v[214:215], v1 offset:0x1e00
	v_mfma_f32_32x32x16_bf16 v[34:49], v[156:159], v[216:219], v[34:49]
	ds_read_b64_tr_b16 v[216:217], v1 offset:0x2600
	ds_read_b64_tr_b16 v[218:219], v1 offset:0x2e00
	ds_read_b64_tr_b16 v[224:225], v1 offset:0x3600
	ds_read_b64_tr_b16 v[226:227], v1 offset:0x3e00
	s_waitcnt lgkmcnt(0)
	v_mfma_f32_32x32x16_bf16 v[34:49], v[208:211], v[220:223], v[34:49]
	s_waitcnt vmcnt(4)
	v_lshrrev_b32_e32 v160, v163, v146
	v_lshrrev_b32_e32 v161, v163, v147
	v_bfe_i32 v146, v160, 0, 1
	v_bfe_i32 v147, v161, 0, 1
	v_bitop3_b32 v146, v66, s74, v146 bitop3:0xe4
	v_bitop3_b32 v66, v82, s74, v147 bitop3:0xe4
	v_bfe_i32 v82, v160, 1, 1
	v_bfe_i32 v147, v161, 1, 1
	v_bitop3_b32 v82, v67, s74, v82 bitop3:0xe4
	v_bitop3_b32 v67, v83, s74, v147 bitop3:0xe4
	v_bfe_i32 v83, v160, 2, 1
	v_bfe_i32 v147, v161, 2, 1
	v_bitop3_b32 v83, v68, s74, v83 bitop3:0xe4
	v_bitop3_b32 v68, v84, s74, v147 bitop3:0xe4
	v_bfe_i32 v84, v160, 3, 1
	v_mfma_f32_32x32x16_bf16 v[18:33], v[148:151], v[172:175], v[18:33]
	v_bfe_i32 v148, v161, 3, 1
	v_bitop3_b32 v147, v69, s74, v84 bitop3:0xe4
	v_bfe_i32 v84, v160, 8, 1
	v_bitop3_b32 v69, v85, s74, v148 bitop3:0xe4
	v_bfe_i32 v85, v161, 8, 1
	v_bitop3_b32 v148, v70, s74, v84 bitop3:0xe4
	v_bfe_i32 v84, v160, 9, 1
	v_bitop3_b32 v70, v86, s74, v85 bitop3:0xe4
	v_bfe_i32 v85, v161, 9, 1
	v_bitop3_b32 v149, v71, s74, v84 bitop3:0xe4
	v_bfe_i32 v84, v160, 10, 1
	v_bitop3_b32 v71, v87, s74, v85 bitop3:0xe4
	v_bfe_i32 v85, v161, 10, 1
	v_bitop3_b32 v87, v72, s74, v84 bitop3:0xe4
	v_bfe_i32 v84, v160, 11, 1
	v_bitop3_b32 v72, v88, s74, v85 bitop3:0xe4
	v_bfe_i32 v85, v161, 11, 1
	v_bitop3_b32 v88, v73, s74, v84 bitop3:0xe4
	v_bfe_i32 v73, v160, 16, 1
	v_bitop3_b32 v84, v89, s74, v85 bitop3:0xe4
	v_bfe_i32 v85, v161, 16, 1
	v_bitop3_b32 v89, v74, s74, v73 bitop3:0xe4
	v_bfe_i32 v73, v160, 17, 1
	v_bfe_i32 v74, v161, 17, 1
	v_bitop3_b32 v85, v90, s74, v85 bitop3:0xe4
	v_bitop3_b32 v90, v75, s74, v73 bitop3:0xe4
	v_bitop3_b32 v86, v91, s74, v74 bitop3:0xe4
	v_bfe_i32 v73, v160, 18, 1
	v_bfe_i32 v74, v161, 18, 1
	v_bitop3_b32 v91, v76, s74, v73 bitop3:0xe4
	v_bitop3_b32 v76, v92, s74, v74 bitop3:0xe4
	v_bfe_i32 v73, v160, 19, 1
	v_bfe_i32 v74, v161, 19, 1
	v_bitop3_b32 v92, v77, s74, v73 bitop3:0xe4
	v_bitop3_b32 v77, v93, s74, v74 bitop3:0xe4
	v_bfe_i32 v73, v160, 24, 1
	v_bfe_i32 v74, v161, 24, 1
	v_bitop3_b32 v93, v78, s74, v73 bitop3:0xe4
	v_bitop3_b32 v78, v94, s74, v74 bitop3:0xe4
	v_bfe_i32 v73, v160, 25, 1
	v_bfe_i32 v74, v161, 25, 1
	v_bitop3_b32 v79, v79, s74, v73 bitop3:0xe4
	v_bitop3_b32 v73, v95, s74, v74 bitop3:0xe4
	v_bfe_i32 v74, v160, 26, 1
	v_bfe_i32 v75, v161, 26, 1
	v_bitop3_b32 v80, v80, s74, v74 bitop3:0xe4
	v_bitop3_b32 v74, v96, s74, v75 bitop3:0xe4
	v_bfe_i32 v75, v160, 27, 1
	v_bfe_i32 v94, v161, 27, 1
	v_bitop3_b32 v81, v81, s74, v75 bitop3:0xe4
	v_bitop3_b32 v75, v97, s74, v94 bitop3:0xe4
	v_max_f32_e32 v94, v82, v82
	v_max_f32_e32 v95, v146, v146
	v_max_f32_e32 v94, v95, v94
	v_max3_f32 v94, v94, v83, v147
	v_max3_f32 v94, v94, v148, v149
	v_max3_f32 v94, v94, v87, v88
	v_max3_f32 v94, v94, v89, v90
	v_mfma_f32_32x32x16_bf16 v[18:33], v[152:155], v[212:215], v[18:33]
	v_max3_f32 v94, v94, v91, v92
	v_max3_f32 v94, v94, v93, v79
	v_max3_f32 v94, v94, v80, v81
	v_max3_f32 v94, v94, v66, v67
	v_max3_f32 v94, v94, v68, v69
	v_max3_f32 v94, v94, v70, v71
	v_max3_f32 v94, v94, v72, v84
	v_max3_f32 v94, v94, v85, v86
	v_mfma_f32_32x32x16_bf16 v[18:33], v[156:159], v[216:219], v[18:33]
	v_max3_f32 v94, v94, v76, v77
	v_max3_f32 v94, v94, v78, v73
	v_max3_f32 v94, v94, v74, v75
	v_mov_b32_e32 v95, v94
	s_nop 1
	v_permlane32_swap_b32_e32 v94, v95
	v_max_f32_e32 v95, v95, v95
	v_max_f32_e32 v94, v94, v94
	v_max_f32_e32 v94, v94, v95
	v_max_f32_e32 v96, v206, v206
	v_sub_f32_e32 v95, v94, v206
	v_max_f32_e32 v94, v96, v94
	v_mfma_f32_32x32x16_bf16 v[18:33], v[208:211], v[224:227], v[18:33]
	v_sub_f32_e32 v96, v206, v94
	v_mul_f32_e32 v96, 0x3e0293ee, v96
	v_mul_f32_e32 v95, 0x3db504f3, v95
	v_exp_f32_e32 v96, v96
	v_cmp_ge_f32_e32 vcc, s75, v95
	s_cmp_eq_u64 vcc, exec
	s_cselect_b64 s[6:7], -1, 0
	s_barrier
	s_waitcnt vmcnt(0)
	v_cndmask_b32_e64 v208, v96, 1.0, s[6:7]
	v_cmp_gt_f32_e32 vcc, 1.0, v208
	ds_write_b128 v197, v[130:133]
	ds_write_b128 v198, v[134:137]
	ds_write_b128 v204, v[138:141] offset:32768
	ds_write_b128 v204, v[142:145] offset:40960
	s_cbranch_vccz .LBB0_1303
	s_and_saveexec_b64 s[36:37], s[0:1]
	ds_write_b32 v185, v208 offset:128
	s_or_b64 exec, exec, s[36:37]
	s_waitcnt lgkmcnt(0)
	ds_read_b128 v[150:153], v183 offset:224
	ds_read_b128 v[154:157], v183 offset:192
	ds_read_b128 v[158:161], v183 offset:160
	ds_read_b128 v[172:175], v183 offset:128
	s_waitcnt lgkmcnt(3)
	v_pk_mul_f32 v[16:17], v[16:17], v[152:153]
	s_waitcnt lgkmcnt(2)
	v_pk_mul_f32 v[12:13], v[12:13], v[156:157]
	s_waitcnt lgkmcnt(1)
	v_pk_mul_f32 v[8:9], v[8:9], v[160:161]
	s_waitcnt lgkmcnt(0)
	v_pk_mul_f32 v[4:5], v[4:5], v[174:175]
	v_pk_mul_f32 v[14:15], v[14:15], v[150:151]
	v_pk_mul_f32 v[10:11], v[10:11], v[154:155]
	v_pk_mul_f32 v[6:7], v[6:7], v[158:159]
	v_pk_mul_f32 v[2:3], v[2:3], v[172:173]
	v_pk_mul_f32 v[64:65], v[64:65], v[152:153]
	v_pk_mul_f32 v[60:61], v[60:61], v[156:157]
	v_pk_mul_f32 v[56:57], v[56:57], v[160:161]
	v_pk_mul_f32 v[52:53], v[52:53], v[174:175]
	v_pk_mul_f32 v[62:63], v[62:63], v[150:151]
	v_pk_mul_f32 v[58:59], v[58:59], v[154:155]
	v_pk_mul_f32 v[54:55], v[54:55], v[158:159]
	v_pk_mul_f32 v[50:51], v[50:51], v[172:173]
	v_pk_mul_f32 v[48:49], v[48:49], v[152:153]
	v_pk_mul_f32 v[44:45], v[44:45], v[156:157]
	v_pk_mul_f32 v[40:41], v[40:41], v[160:161]
	v_pk_mul_f32 v[36:37], v[36:37], v[174:175]
	v_pk_mul_f32 v[46:47], v[46:47], v[150:151]
	v_pk_mul_f32 v[42:43], v[42:43], v[154:155]
	v_pk_mul_f32 v[38:39], v[38:39], v[158:159]
	v_pk_mul_f32 v[34:35], v[34:35], v[172:173]
	v_pk_mul_f32 v[32:33], v[32:33], v[152:153]
	v_pk_mul_f32 v[28:29], v[28:29], v[156:157]
	v_pk_mul_f32 v[24:25], v[24:25], v[160:161]
	v_pk_mul_f32 v[20:21], v[20:21], v[174:175]
	v_pk_mul_f32 v[30:31], v[30:31], v[150:151]
	v_pk_mul_f32 v[26:27], v[26:27], v[154:155]
	v_pk_mul_f32 v[22:23], v[22:23], v[158:159]
	v_pk_mul_f32 v[18:19], v[18:19], v[172:173]
